# P5 exchange poll: wave-uniform all-ready test done on the scalar unit (s_andn2 + scc branch) instead of v_cndmask/v_cmp/s_cmp
# speedup vs baseline: 1.0042x; 1.0042x over previous
;     __device__ __forceinline__ void fused(f32x4 (&acc)[2][2][4][2], const Unit& u, int wr, int wc, int fr, int fq, PG8_LAS unsigned char* lds, int wid, int lane) const {
;     ...
;           for (;;) { bool ok = true; q = 0.f;
;             if (lane < 32) {
; #pragma unroll
;               for (int t = 0; t < 8; ++t) { const unsigned v_ = __hip_atomic_load(slotu + t, __ATOMIC_RELAXED, __HIP_MEMORY_SCOPE_AGENT); ok = ok && (v_ != 0u); q += __uint_as_float(v_); } }
;             if (__all(ok)) break;
;             if (__builtin_amdgcn_s_memrealtime() - t0 > 2000000ull) { if (lane == 0) __hip_atomic_store(tmo, 1u, __ATOMIC_RELAXED, __HIP_MEMORY_SCOPE_AGENT); dead = true; break; }
;             __builtin_amdgcn_s_sleep(2); }
.LBB0_1057:
	s_or_b64 exec, exec, s[22:23]
	s_andn2_b64 vcc, exec, s[4:5]
	s_mov_b64 s[4:5], 0
	s_cbranch_scc0 .LBB0_1054
	s_memrealtime s[6:7]
	s_mov_b64 s[4:5], -1
	s_waitcnt lgkmcnt(0)
	s_sub_u32 s6, s6, s18
	s_subb_u32 s7, s7, s19
	v_cmp_lt_u64_e32 vcc, s[6:7], v[2:3]
	s_mov_b64 s[6:7], -1
	s_cbranch_vccz .LBB0_1060
	s_sleep 2
	s_mov_b64 s[6:7], 0
